# P0 bias dot product (workgroups 0-31, before the grid sync): 32 serialized load-wait-fmac round trips replaced by 64 loads up front and 32 in-order fmacs
# speedup vs baseline: 1.0283x; 1.0012x over previous
; DI void prologue(const Params& p, LAS unsigned char* lds, int tid, int lane, int wave) {
;     ...
;     if (gw < 256) {
;         const int which = gw >> 7, j = gw & 127;
;         const float* W = which ? p.in[12] : p.in[10]; const float* pe = which ? p.in[9] : p.in[8];
;         float s = 0.f;
;         for (int k = lane; k < 2048; k += 64) s += pe[k] * W[(size_t)k * 128 + j];
;         s = wave_sum(s);
;         if (lane == 0) { BIAS[which * 256 + j] = s; BIAS[which * 256 + 128 + j] = 0.f; }
.LBB0_128:
	global_load_dword v64, v[8:9], off
	global_load_dword v96, v[10:11], off
	v_lshl_add_u64 v[10:11], v[10:11], 0, s[16:17]
	global_load_dword v65, v[8:9], off offset:256
	global_load_dword v97, v[10:11], off
	v_lshl_add_u64 v[10:11], v[10:11], 0, s[16:17]
	global_load_dword v66, v[8:9], off offset:512
	global_load_dword v98, v[10:11], off
	v_lshl_add_u64 v[10:11], v[10:11], 0, s[16:17]
	global_load_dword v67, v[8:9], off offset:768
	global_load_dword v99, v[10:11], off
	v_lshl_add_u64 v[10:11], v[10:11], 0, s[16:17]
	global_load_dword v68, v[8:9], off offset:1024
	global_load_dword v100, v[10:11], off
	v_lshl_add_u64 v[10:11], v[10:11], 0, s[16:17]
	global_load_dword v69, v[8:9], off offset:1280
	global_load_dword v101, v[10:11], off
	v_lshl_add_u64 v[10:11], v[10:11], 0, s[16:17]
	global_load_dword v70, v[8:9], off offset:1536
	global_load_dword v102, v[10:11], off
	v_lshl_add_u64 v[10:11], v[10:11], 0, s[16:17]
	global_load_dword v71, v[8:9], off offset:1792
	global_load_dword v103, v[10:11], off
	v_lshl_add_u64 v[10:11], v[10:11], 0, s[16:17]
	global_load_dword v72, v[8:9], off offset:2048
	global_load_dword v104, v[10:11], off
	v_lshl_add_u64 v[10:11], v[10:11], 0, s[16:17]
	global_load_dword v73, v[8:9], off offset:2304
	global_load_dword v105, v[10:11], off
	v_lshl_add_u64 v[10:11], v[10:11], 0, s[16:17]
	global_load_dword v74, v[8:9], off offset:2560
	global_load_dword v106, v[10:11], off
	v_lshl_add_u64 v[10:11], v[10:11], 0, s[16:17]
	global_load_dword v75, v[8:9], off offset:2816
	global_load_dword v107, v[10:11], off
	v_lshl_add_u64 v[10:11], v[10:11], 0, s[16:17]
	global_load_dword v76, v[8:9], off offset:3072
	global_load_dword v108, v[10:11], off
	v_lshl_add_u64 v[10:11], v[10:11], 0, s[16:17]
	global_load_dword v77, v[8:9], off offset:3328
	global_load_dword v109, v[10:11], off
	v_lshl_add_u64 v[10:11], v[10:11], 0, s[16:17]
	global_load_dword v78, v[8:9], off offset:3584
	global_load_dword v110, v[10:11], off
	v_lshl_add_u64 v[10:11], v[10:11], 0, s[16:17]
	global_load_dword v79, v[8:9], off offset:3840
	global_load_dword v111, v[10:11], off
	v_lshl_add_u64 v[10:11], v[10:11], 0, s[16:17]
	v_add_co_u32_e32 v8, vcc, 0x1000, v8
	s_nop 1
	v_addc_co_u32_e32 v9, vcc, 0, v9, vcc
	global_load_dword v80, v[8:9], off
	global_load_dword v112, v[10:11], off
	v_lshl_add_u64 v[10:11], v[10:11], 0, s[16:17]
	global_load_dword v81, v[8:9], off offset:256
	global_load_dword v113, v[10:11], off
	v_lshl_add_u64 v[10:11], v[10:11], 0, s[16:17]
	global_load_dword v82, v[8:9], off offset:512
	global_load_dword v114, v[10:11], off
	v_lshl_add_u64 v[10:11], v[10:11], 0, s[16:17]
	global_load_dword v83, v[8:9], off offset:768
	global_load_dword v115, v[10:11], off
	v_lshl_add_u64 v[10:11], v[10:11], 0, s[16:17]
	global_load_dword v84, v[8:9], off offset:1024
	global_load_dword v116, v[10:11], off
	v_lshl_add_u64 v[10:11], v[10:11], 0, s[16:17]
	global_load_dword v85, v[8:9], off offset:1280
	global_load_dword v117, v[10:11], off
	v_lshl_add_u64 v[10:11], v[10:11], 0, s[16:17]
	global_load_dword v86, v[8:9], off offset:1536
	global_load_dword v118, v[10:11], off
	v_lshl_add_u64 v[10:11], v[10:11], 0, s[16:17]
	global_load_dword v87, v[8:9], off offset:1792
	global_load_dword v119, v[10:11], off
	v_lshl_add_u64 v[10:11], v[10:11], 0, s[16:17]
	global_load_dword v88, v[8:9], off offset:2048
	global_load_dword v120, v[10:11], off
	v_lshl_add_u64 v[10:11], v[10:11], 0, s[16:17]
	global_load_dword v89, v[8:9], off offset:2304
	global_load_dword v121, v[10:11], off
	v_lshl_add_u64 v[10:11], v[10:11], 0, s[16:17]
	global_load_dword v90, v[8:9], off offset:2560
	global_load_dword v122, v[10:11], off
	v_lshl_add_u64 v[10:11], v[10:11], 0, s[16:17]
	global_load_dword v91, v[8:9], off offset:2816
	global_load_dword v123, v[10:11], off
	v_lshl_add_u64 v[10:11], v[10:11], 0, s[16:17]
	global_load_dword v92, v[8:9], off offset:3072
	global_load_dword v124, v[10:11], off
	v_lshl_add_u64 v[10:11], v[10:11], 0, s[16:17]
	global_load_dword v93, v[8:9], off offset:3328
	global_load_dword v125, v[10:11], off
	v_lshl_add_u64 v[10:11], v[10:11], 0, s[16:17]
	global_load_dword v94, v[8:9], off offset:3584
	global_load_dword v126, v[10:11], off
	v_lshl_add_u64 v[10:11], v[10:11], 0, s[16:17]
	global_load_dword v95, v[8:9], off offset:3840
	global_load_dword v127, v[10:11], off
	s_waitcnt vmcnt(62)
; DI float wave_sum(float v) {
; #pragma unroll
;     for (int o = 1; o < 64; o <<= 1) v += __shfl_xor(v, o);
;     return v;
; }
; DI void prologue(const Params& p, LAS unsigned char* lds, int tid, int lane, int wave) {
;     ...
;         for (int k = lane; k < 2048; k += 64) s += pe[k] * W[(size_t)k * 128 + j];
;         s = wave_sum(s);
;         if (lane == 0) { BIAS[which * 256 + j] = s; BIAS[which * 256 + 128 + j] = 0.f; }
	v_fmac_f32_e32 v7, v64, v96
	s_waitcnt vmcnt(60)
	v_fmac_f32_e32 v7, v65, v97
	s_waitcnt vmcnt(58)
	v_fmac_f32_e32 v7, v66, v98
	s_waitcnt vmcnt(56)
	v_fmac_f32_e32 v7, v67, v99
	s_waitcnt vmcnt(54)
	v_fmac_f32_e32 v7, v68, v100
	s_waitcnt vmcnt(52)
	v_fmac_f32_e32 v7, v69, v101
	s_waitcnt vmcnt(50)
	v_fmac_f32_e32 v7, v70, v102
	s_waitcnt vmcnt(48)
	v_fmac_f32_e32 v7, v71, v103
	s_waitcnt vmcnt(46)
	v_fmac_f32_e32 v7, v72, v104
	s_waitcnt vmcnt(44)
	v_fmac_f32_e32 v7, v73, v105
	s_waitcnt vmcnt(42)
	v_fmac_f32_e32 v7, v74, v106
	s_waitcnt vmcnt(40)
	v_fmac_f32_e32 v7, v75, v107
	s_waitcnt vmcnt(38)
	v_fmac_f32_e32 v7, v76, v108
	s_waitcnt vmcnt(36)
	v_fmac_f32_e32 v7, v77, v109
	s_waitcnt vmcnt(34)
	v_fmac_f32_e32 v7, v78, v110
	s_waitcnt vmcnt(32)
	v_fmac_f32_e32 v7, v79, v111
	s_waitcnt vmcnt(30)
	v_fmac_f32_e32 v7, v80, v112
	s_waitcnt vmcnt(28)
	v_fmac_f32_e32 v7, v81, v113
	s_waitcnt vmcnt(26)
	v_fmac_f32_e32 v7, v82, v114
	s_waitcnt vmcnt(24)
	v_fmac_f32_e32 v7, v83, v115
	s_waitcnt vmcnt(22)
	v_fmac_f32_e32 v7, v84, v116
	s_waitcnt vmcnt(20)
	v_fmac_f32_e32 v7, v85, v117
	s_waitcnt vmcnt(18)
	v_fmac_f32_e32 v7, v86, v118
	s_waitcnt vmcnt(16)
	v_fmac_f32_e32 v7, v87, v119
	s_waitcnt vmcnt(14)
	v_fmac_f32_e32 v7, v88, v120
	s_waitcnt vmcnt(12)
	v_fmac_f32_e32 v7, v89, v121
	s_waitcnt vmcnt(10)
	v_fmac_f32_e32 v7, v90, v122
	s_waitcnt vmcnt(8)
	v_fmac_f32_e32 v7, v91, v123
	s_waitcnt vmcnt(6)
	v_fmac_f32_e32 v7, v92, v124
	s_waitcnt vmcnt(4)
	v_fmac_f32_e32 v7, v93, v125
	s_waitcnt vmcnt(2)
	v_fmac_f32_e32 v7, v94, v126
	s_waitcnt vmcnt(0)
	v_fmac_f32_e32 v7, v95, v127
	s_or_b64 exec, exec, s[0:1]
	v_mbcnt_hi_u32_b32 v5, -1, v169
	v_and_b32_e32 v3, 64, v5
	v_add_u32_e32 v6, 64, v3
	v_xor_b32_e32 v3, 1, v5
	v_cmp_lt_i32_e32 vcc, v3, v6
	v_xor_b32_e32 v8, 2, v5
	s_nop 0
	v_cndmask_b32_e32 v3, v5, v3, vcc
	v_lshlrev_b32_e32 v3, 2, v3
	ds_bpermute_b32 v3, v3, v7
	v_cmp_lt_i32_e32 vcc, v8, v6
	s_waitcnt lgkmcnt(0)
	v_add_f32_e32 v3, v7, v3
	v_cndmask_b32_e32 v7, v5, v8, vcc
	v_lshlrev_b32_e32 v7, 2, v7
	ds_bpermute_b32 v7, v7, v3
	v_xor_b32_e32 v8, 4, v5
	v_cmp_lt_i32_e32 vcc, v8, v6
	s_waitcnt lgkmcnt(0)
	v_add_f32_e32 v3, v3, v7
	v_cndmask_b32_e32 v7, v5, v8, vcc
	v_lshlrev_b32_e32 v7, 2, v7
	ds_bpermute_b32 v7, v7, v3
	v_xor_b32_e32 v8, 8, v5
	v_cmp_lt_i32_e32 vcc, v8, v6
	s_waitcnt lgkmcnt(0)
	v_add_f32_e32 v3, v3, v7
	v_cndmask_b32_e32 v7, v5, v8, vcc
	v_lshlrev_b32_e32 v7, 2, v7
	ds_bpermute_b32 v7, v7, v3
	v_xor_b32_e32 v8, 16, v5
	v_cmp_lt_i32_e32 vcc, v8, v6
	s_waitcnt lgkmcnt(0)
	v_add_f32_e32 v3, v3, v7
	v_cndmask_b32_e32 v7, v5, v8, vcc
	v_lshlrev_b32_e32 v7, 2, v7
	ds_bpermute_b32 v7, v7, v3
	v_xor_b32_e32 v8, 32, v5
	v_cmp_lt_i32_e32 vcc, v8, v6
	s_waitcnt lgkmcnt(0)
	v_add_f32_e32 v3, v3, v7
	v_cndmask_b32_e32 v5, v5, v8, vcc
	v_lshlrev_b32_e32 v5, 2, v5
	ds_bpermute_b32 v5, v5, v3
	v_cmp_eq_u32_e32 vcc, 0, v1
	s_and_saveexec_b64 s[0:1], vcc
	s_cbranch_execz .LBB0_131
	s_lshl_b32 s2, s6, 1
	s_and_b32 s2, s2, 0xffffff00
	s_or_b32 s2, s2, s7
	s_ashr_i32 s3, s2, 31
	s_lshl_b64 s[2:3], s[2:3], 2
	s_add_u32 s2, s8, s2
	s_waitcnt lgkmcnt(0)
	v_add_f32_e32 v1, v3, v5
	s_addc_u32 s3, s9, s3
	v_mov_b32_e32 v3, 0
	global_store_dword v3, v1, s[2:3]
	global_store_dword v3, v3, s[2:3] offset:512
